# deferred weight conversion: only W_in[0] converted in the prologue phase; the other 7 weight copies are made inside layer 0 in-projection phase, XCDs 0-3 before their GEMM units and XCDs 4-7 after the
# speedup vs baseline: 1.0093x; 1.0093x over previous
; #define LAS __attribute__((address_space(3)))
; template <int MODE, int K, int N>
; __device__ __forceinline__ void conv_blocked(const float* __restrict__ W, bf16* D, const float* __restrict__ gk, unsigned gtid, unsigned nthr, LAS unsigned char* scr  ) {
;     constexpr unsigned items = (unsigned)(K >> 5) * (unsigned)N;
;     const int lane = (int)(gtid & 63u);
;     for (unsigned it = gtid; it < items; it += nthr) {
; __device__ __forceinline__ void p0_prologue(const __attribute__((address_space(4))) Args* ka, unsigned char* ws, unsigned gtid, unsigned nthr, int gw, int ngw, int lane, LAS unsigned char* scr) {
;     ...
;     for (int l2 = 0; l2 < DEPTH * PROBE_P0; ++l2) { const int l = DEPTH - 1 - (l2 % DEPTH);
;         unsigned char* wl = ws + WS_W + (size_t)l * W_LAYER;
;         conv_blocked<0, DFF, DM>(in[11] + (size_t)l * DFF * DM, (bf16*)(wl + W_DN), nullptr, gtid, nthr, scr);
;         conv_blocked<0, DM, DFF>(in[10] + (size_t)l * DM * DFF, (bf16*)(wl + W_UP), in[4] + l * DM, gtid, nthr, scr);
;         conv_blocked<0, DM, DM>(in[2] + (size_t)l * DM * DM, (bf16*)(wl + W_OUT), nullptr, gtid, nthr, scr);
;         conv_blocked<1, DM, NIN>(in[1] + (size_t)l * DM * NIN, (bf16*)(wl + W_IN), in[3] + l * DM, gtid, nthr, scr);
.LBB0_33:
	s_or_b64 exec, exec, s[2:3]
	s_ashr_i32 s57, s46, 6
	s_lshl_b32 s2, s57, 12
	v_lshrrev_b32_e32 v4, 1, v1
	s_waitcnt lgkmcnt(0)
	s_add_i32 s10, s2, 0
	v_lshlrev_b32_e32 v3, 2, v1
	v_and_b32_e32 v4, 12, v4
	s_add_u32 s58, s24, 0x2000000
	v_and_b32_e32 v3, 16, v3
	v_and_or_b32 v4, v22, 3, v4
	v_and_b32_e32 v5, 32, v22
	s_addc_u32 s59, s25, 0
	v_or3_b32 v3, v5, v3, v4
	v_and_b32_e32 v2, 63, v22
	v_lshl_add_u32 v6, v3, 6, s10
	v_lshlrev_b32_e32 v3, 1, v1
	s_cmp_lg_u64 s[26:27], 0
	s_mov_b32 s2, 0x200000
	v_and_b32_e32 v8, 32, v3
	v_lshlrev_b32_e32 v4, 4, v2
	v_mov_b32_e32 v7, 0
	v_bitop3_b32 v9, v3, 32, v3 bitop3:0xc
	s_cselect_b64 s[30:31], -1, 0
	s_mov_b32 s60, 0x80000
	s_mov_b32 s61, 0x140000
	s_cmp_lg_u64 s[18:19], 0
	v_lshlrev_b32_e32 v3, 5, v22
	s_mov_b32 s29, 0
	v_cmp_gt_u32_e64 s[4:5], s2, v1
	s_mov_b32 s28, 1
	v_mov_b32_e32 v5, v7
	v_cmp_gt_u32_e64 s[6:7], s60, v1
	v_cmp_gt_u32_e64 s[8:9], s61, v1
	s_cselect_b64 s[34:35], -1, 0
	v_lshl_add_u32 v3, s33, 14, v3
	s_lshl_b32 s62, s1, 14
	v_sub_u32_e32 v44, 0, v2
	s_mov_b64 s[2:3], -1
	s_mov_b64 s[36:37], 0xf000000
	v_add_u32_e32 v45, v6, v8
	v_add_u32_e32 v46, v6, v9
	s_mov_b32 s63, 0x1fffff
	s_mov_b64 s[38:39], 0x7000000
	s_mov_b32 s64, 0xa0000
	s_mov_b32 s65, 0xf0000
	s_mov_b64 s[40:41], 0x5000000
	s_mov_b32 s66, 0x7ffff
	s_mov_b32 s67, 0xcccccccd
	s_movk_i32 s68, 0xd800
	s_movk_i32 s69, 0x3ff
	s_movk_i32 s70, 0x60
	s_mov_b32 s71, 0x13ffff
	v_add_u32_e32 v47, s10, v4
	v_mov_b32_e32 v48, 0x7c
	s_mov_b64 s[4:5], 0
	s_mov_b64 s[6:7], 0
	s_branch .LBB0_35

; __device__ __forceinline__ void p0_prologue(const __attribute__((address_space(4))) Args* ka, unsigned char* ws, unsigned gtid, unsigned nthr, int gw, int ngw, int lane, LAS unsigned char* scr) {
;     ...
;     for (int l2 = 0; l2 < DEPTH * PROBE_P0; ++l2) { const int l = DEPTH - 1 - (l2 % DEPTH);
;         unsigned char* wl = ws + WS_W + (size_t)l * W_LAYER;
;         conv_blocked<0, DFF, DM>(in[11] + (size_t)l * DFF * DM, (bf16*)(wl + W_DN), nullptr, gtid, nthr, scr);
;         conv_blocked<0, DM, DFF>(in[10] + (size_t)l * DM * DFF, (bf16*)(wl + W_UP), in[4] + l * DM, gtid, nthr, scr);
;         conv_blocked<0, DM, DM>(in[2] + (size_t)l * DM * DM, (bf16*)(wl + W_OUT), nullptr, gtid, nthr, scr);
;         conv_blocked<1, DM, NIN>(in[1] + (size_t)l * DM * NIN, (bf16*)(wl + W_IN), in[3] + l * DM, gtid, nthr, scr);
.LBB0_46:
	s_or_b64 exec, exec, s[2:3]
	s_cmp_eq_u32 s28, 1
	s_cselect_b64 s[98:99], 0, s[8:9]
	s_and_saveexec_b64 s[44:45], s[98:99]
	s_cbranch_execz .LBB0_34
	s_mul_i32 s2, s28, 0xa000000
	s_add_u32 s46, s14, s2
	s_addc_u32 s47, s15, 0
	s_lshl_b64 s[2:3], s[10:11], 2
	s_add_u32 s48, s18, s2
	s_addc_u32 s49, s19, s3
	s_mov_b64 s[50:51], 0
	v_mov_b32_e32 v42, v1
	s_branch .LBB0_51

; #define REP(b) for (int rep_ = 0; rep_ < (((DUPMASK >> (b)) & 1) ? 2 : 1); ++rep_)
; #define SEAM(k) do { if (IN(k) && IN((k) + 1)) { XcdBarrier bar_; bar_.bar = (unsigned*)(kargs()->ws + WS_CTL) + CW_BAR; bar_.x = xb_xcc_id(); bar_.st = (volatile LAS unsigned*)(ldsp + MISC_OFF) + 8; xcd_barrier(bar_); } } while (0)
; __global__ void __launch_bounds__(NWAVES * 64, 2) fwd(Args args_unused) {
;     ...
;     if (IN(0)) { REP(0) { ENV(); p0_prologue(ka, ws, gtid, nthr, gw, ngw, lane, ldsp + RING_OFF + wave * 4096); } SEAM(0);
.LBB0_272:
	s_andn2_b64 vcc, exec, s[4:5]
	s_cbranch_vccnz .LBB0_354
	s_cmp_lg_u32 s71, 0
	s_cbranch_scc1 .Ldefer_skipA
	s_bitcmp0_b32 s77, 2
	s_cbranch_scc0 .Ldefer_skipA
	v_writelane_b32 v252, s12, 0
	v_writelane_b32 v252, s13, 1
	v_writelane_b32 v252, s33, 2
	v_writelane_b32 v252, s56, 3
	v_writelane_b32 v252, s57, 4
	v_writelane_b32 v252, s58, 5
	v_writelane_b32 v252, s59, 6
	v_writelane_b32 v252, s60, 7
	v_writelane_b32 v252, s61, 8
	v_writelane_b32 v252, s62, 9
	v_writelane_b32 v252, s63, 10
	v_writelane_b32 v252, s64, 11
	v_writelane_b32 v252, s65, 12
	v_writelane_b32 v252, s66, 13
	v_writelane_b32 v252, s67, 14
	v_writelane_b32 v252, s68, 15
	v_writelane_b32 v252, s69, 16
	v_writelane_b32 v252, s70, 17
	v_writelane_b32 v252, s71, 18
	v_writelane_b32 v252, s72, 19
	s_add_u32 s90, s84, 0x80
	s_addc_u32 s91, s85, 0
	s_add_i32 s0, 0, 0x20188
	s_mov_b64 s[2:3], s[84:85]
	v_mov_b32_e32 v22, v0
	v_mov_b32_e32 v1, s0
	s_load_dwordx2 s[24:25], s[2:3], 0x70
	s_load_dword s1, s[84:85], 0x80
	ds_read_b32 v1, v1
	v_readfirstlane_b32 s46, v22
	s_mov_b32 s33, s77
	s_waitcnt lgkmcnt(0)
	v_cmp_eq_u32_e32 vcc, 0, v1
	s_cbranch_vccnz .Lca_22
	s_add_i32 s0, 0, 0x20184
	v_mov_b32_e32 v1, s0
	s_add_i32 s0, 0, 0x20180
	ds_read_b32 v1, v1
	v_mov_b32_e32 v2, s0
	ds_read_b32 v2, v2
	s_waitcnt lgkmcnt(1)
	v_readfirstlane_b32 s0, v1
	s_lshl_b32 s0, s0, 3
	s_waitcnt lgkmcnt(0)
	v_readfirstlane_b32 s4, v2
	s_add_i32 s33, s0, s4

; #define LAS __attribute__((address_space(3)))
; __device__ __forceinline__ void p0_prologue(const __attribute__((address_space(4))) Args* ka, unsigned char* ws, unsigned gtid, unsigned nthr, int gw, int ngw, int lane, LAS unsigned char* scr) {
;     const float* in[13];
; #pragma unroll
;     for (int i = 0; i < 13; ++i) in[i] = ka->in[i];
;     { float* cosA = (float*)(ws + WS_COSA); float* sinA = (float*)(ws + WS_SINA); float* cosB = (float*)(ws + WS_COSB); float* sinB = (float*)(ws + WS_SINB);
;       for (unsigned it = gtid; it < (unsigned)SEQ * 96u; it += nthr) { const unsigned pos = it / 96u, j = it - pos * 96u; const bool isA = j < 32u; const int i = isA ? (int)j : (int)j - 32;
;           const double inv = exp2(-(double)i * (isA ? (1.0 / 32.0) : (1.0 / 64.0)) * 13.287712379549449);
;           double rev = (double)pos * inv * 0.15915494309189535; rev -= rint(rev);
;           const float rv = (float)rev, c = __builtin_amdgcn_cosf(rv), s = __builtin_amdgcn_sinf(rv);
;           if (isA) { cosA[pos * 32 + i] = c; sinA[pos * 32 + i] = s; } else { cosB[pos * 64 + i] = c; sinB[pos * 64 + i] = s; } } }
.Lca_24:
	s_load_dwordx8 s[12:19], s[2:3], 0x0
	s_load_dwordx2 s[26:27], s[2:3], 0x20
	s_load_dwordx4 s[8:11], s[2:3], 0x38
	s_load_dwordx4 s[20:23], s[2:3], 0x50
	s_lshl_b32 s56, s33, 9
	v_add_u32_e32 v1, s56, v22
	s_mov_b32 s2, 0x60000
	s_lshl_b32 s0, s1, 9
	v_cmp_gt_u32_e32 vcc, s2, v1
	s_mov_b64 s[2:3], exec
	s_branch .Lca_33
	s_mov_b32 s30, 0x979a371
	s_mov_b32 s34, 0x3b39803f
	s_mov_b32 s36, 0xfefa39ef
	s_mov_b32 s38, 0x6a5dcb37
	s_mov_b32 s40, 0
	s_mov_b32 s42, 0
	s_mov_b32 s44, 0x6dc9c883
	s_mov_b64 s[28:29], 0
	s_mov_b32 s47, 0xaaaaaaab
	s_movk_i32 s48, 0xffa0
	v_mov_b32_e32 v23, 0x3f900000
	v_mov_b32_e32 v24, 0x3fa00000
	v_mov_b32_e32 v2, 0
	s_mov_b32 s31, 0xc02a934f
	s_mov_b32 s35, 0x3c7abc9e
	s_mov_b32 s37, 0x3fe62e42
	v_mov_b32_e32 v4, 0xfca7ab0c
	v_mov_b32_e32 v5, 0x3e928af3
	s_mov_b32 s39, 0x3e5ade15
	v_mov_b32_e32 v6, 0x623fde64
	v_mov_b32_e32 v7, 0x3ec71dee
	v_mov_b32_e32 v8, 0x7c89e6b0
	v_mov_b32_e32 v9, 0x3efa0199
	v_mov_b32_e32 v10, 0x14761f6e
	v_mov_b32_e32 v11, 0x3f2a01a0
	v_mov_b32_e32 v12, 0x1852b7b0
	v_mov_b32_e32 v13, 0x3f56c16c
	v_mov_b32_e32 v14, 0x11122322
	v_mov_b32_e32 v15, 0x3f811111
	v_mov_b32_e32 v16, 0x555502a1
	v_mov_b32_e32 v17, 0x3fa55555
	v_mov_b32_e32 v18, 0x55555511
	v_mov_b32_e32 v19, 0x3fc55555
	v_mov_b32_e32 v20, 11
	v_mov_b32_e32 v21, 0x3fe00000
	s_mov_b32 s41, 0x40900000
	v_mov_b32_e32 v25, 0x7ff00000
	s_mov_b32 s43, 0xc090cc00
	s_mov_b32 s45, 0x3fc45f30
	s_movk_i32 s49, 0xffe0
	v_mov_b32_e32 v26, 0x200000
	v_mov_b32_e32 v27, 0x100000
	v_mov_b32_e32 v28, 0x300000
	v_mov_b32_e32 v29, 0x180000
	s_mov_b32 s50, 0x5ffff
	v_mov_b32_e32 v30, v1

; __device__ __forceinline__ void p0_prologue(const __attribute__((address_space(4))) Args* ka, unsigned char* ws, unsigned gtid, unsigned nthr, int gw, int ngw, int lane, LAS unsigned char* scr) {
;     ...
;     for (int l2 = 0; l2 < DEPTH * PROBE_P0; ++l2) { const int l = DEPTH - 1 - (l2 % DEPTH);
;         unsigned char* wl = ws + WS_W + (size_t)l * W_LAYER;
;         conv_blocked<0, DFF, DM>(in[11] + (size_t)l * DFF * DM, (bf16*)(wl + W_DN), nullptr, gtid, nthr, scr);
;         conv_blocked<0, DM, DFF>(in[10] + (size_t)l * DM * DFF, (bf16*)(wl + W_UP), in[4] + l * DM, gtid, nthr, scr);
;         conv_blocked<0, DM, DM>(in[2] + (size_t)l * DM * DM, (bf16*)(wl + W_OUT), nullptr, gtid, nthr, scr);
;         conv_blocked<1, DM, NIN>(in[1] + (size_t)l * DM * NIN, (bf16*)(wl + W_IN), in[3] + l * DM, gtid, nthr, scr);
.Lca_46:
	s_or_b64 exec, exec, s[2:3]
	s_cmp_eq_u32 s28, 0
	s_cselect_b64 s[98:99], 0, s[8:9]
	s_and_saveexec_b64 s[44:45], s[98:99]
	s_cbranch_execz .Lca_34
	s_mul_i32 s2, s28, 0xa000000
	s_add_u32 s46, s14, s2
	s_addc_u32 s47, s15, 0
	s_lshl_b64 s[2:3], s[10:11], 2
	s_add_u32 s48, s18, s2
	s_addc_u32 s49, s19, s3
	s_mov_b64 s[50:51], 0
	v_mov_b32_e32 v42, v1
	s_branch .Lca_51

; #define REP(b) for (int rep_ = 0; rep_ < (((DUPMASK >> (b)) & 1) ? 2 : 1); ++rep_)
; __global__ void __launch_bounds__(NWAVES * 64, 2) fwd(Args args_unused) {
;     ...
;         if (IN(pb)) {
;             REP(2) { ENV(); pg8::Gemm g{(const bf16*)(ws + WS_HN), (const bf16*)(ws + WS_W + (size_t)l * W_LAYER + W_IN), M, NIN, DM, LDH, 0}; pg8::StaticOrder S; S.init(M, NIN, G, bx);
;               pg8::EpiProj E{(bf16*)(ws + WS_PROJ), (const float*)(ws + WS_COSA), (const float*)(ws + WS_SINA), (const float*)(ws + WS_COSB), (const float*)(ws + WS_SINB), (const pg8::ss_t*)(ws + WS_SS) + l * M};
;               pg8::gemm_phase<pg8::EpiProj, pg8::StaticOrder, true>(ldsp + RING_OFF, g, S, E); }
.Lca_end:
	s_waitcnt lgkmcnt(0)
	s_barrier
	v_readlane_b32 s12, v252, 0
	v_readlane_b32 s13, v252, 1
	v_readlane_b32 s33, v252, 2
	v_readlane_b32 s56, v252, 3
	v_readlane_b32 s57, v252, 4
	v_readlane_b32 s58, v252, 5
	v_readlane_b32 s59, v252, 6
	v_readlane_b32 s60, v252, 7
	v_readlane_b32 s61, v252, 8
	v_readlane_b32 s62, v252, 9
	v_readlane_b32 s63, v252, 10
	v_readlane_b32 s64, v252, 11
	v_readlane_b32 s65, v252, 12
	v_readlane_b32 s66, v252, 13
	v_readlane_b32 s67, v252, 14
	v_readlane_b32 s68, v252, 15
	v_readlane_b32 s69, v252, 16
	v_readlane_b32 s70, v252, 17
	v_readlane_b32 s71, v252, 18
	v_readlane_b32 s72, v252, 19
	v_mov_b32_e32 v1, 0x358637bd
	s_nop 4
.Ldefer_skipA:
	s_mov_b64 s[0:1], s[84:85]
	s_waitcnt vmcnt(0)
	v_mov_b32_e32 v2, v0
	s_load_dwordx2 s[14:15], s[0:1], 0x70
	s_load_dword s3, s[90:91], 0x0
	v_mov_b32_e32 v2, s60
	ds_read_b32 v2, v2
	s_mov_b32 s38, s77
	s_waitcnt lgkmcnt(0)
	v_cmp_eq_u32_e32 vcc, 0, v2
	s_cbranch_vccnz .LBB0_275
	v_mov_b32_e32 v2, s61
	ds_read_b32 v2, v2
	v_mov_b32_e32 v3, s62
	ds_read_b32 v3, v3
	s_waitcnt lgkmcnt(0)
	v_readfirstlane_b32 s0, v2
	s_lshl_b32 s0, s0, 3
	v_readfirstlane_b32 s1, v3
	s_add_i32 s38, s0, s1

; #define SEAM(k) do { if (IN(k) && IN((k) + 1)) { XcdBarrier bar_; bar_.bar = (unsigned*)(kargs()->ws + WS_CTL) + CW_BAR; bar_.x = xb_xcc_id(); bar_.st = (volatile LAS unsigned*)(ldsp + MISC_OFF) + 8; xcd_barrier(bar_); } } while (0)
; __global__ void __launch_bounds__(NWAVES * 64, 2) fwd(Args args_unused) {
;     ...
;               pg8::gemm_phase<pg8::EpiProj, pg8::StaticOrder, true>(ldsp + RING_OFF, g, S, E); }
;             SEAM(pb);
.LBB0_300:
	s_cmp_lg_u32 s71, 0
	s_cbranch_scc1 .Ldefer_skipB
	s_bitcmp1_b32 s77, 2
	s_cbranch_scc0 .Ldefer_skipB
	v_writelane_b32 v252, s12, 0
	v_writelane_b32 v252, s13, 1
	v_writelane_b32 v252, s33, 2
	v_writelane_b32 v252, s56, 3
	v_writelane_b32 v252, s57, 4
	v_writelane_b32 v252, s58, 5
	v_writelane_b32 v252, s59, 6
	v_writelane_b32 v252, s60, 7
	v_writelane_b32 v252, s61, 8
	v_writelane_b32 v252, s62, 9
	v_writelane_b32 v252, s63, 10
	v_writelane_b32 v252, s64, 11
	v_writelane_b32 v252, s65, 12
	v_writelane_b32 v252, s66, 13
	v_writelane_b32 v252, s67, 14
	v_writelane_b32 v252, s68, 15
	v_writelane_b32 v252, s69, 16
	v_writelane_b32 v252, s70, 17
	v_writelane_b32 v252, s71, 18
	v_writelane_b32 v252, s72, 19
	s_add_u32 s90, s84, 0x80
	s_addc_u32 s91, s85, 0
	s_add_i32 s0, 0, 0x20188
	s_mov_b64 s[2:3], s[84:85]
	v_mov_b32_e32 v22, v0
	v_mov_b32_e32 v1, s0
	s_load_dwordx2 s[24:25], s[2:3], 0x70
	s_load_dword s1, s[84:85], 0x80
	ds_read_b32 v1, v1
	v_readfirstlane_b32 s46, v22
	s_mov_b32 s33, s77
	s_waitcnt lgkmcnt(0)
	v_cmp_eq_u32_e32 vcc, 0, v1
	s_cbranch_vccnz .Lcb_22
	s_add_i32 s0, 0, 0x20184
	v_mov_b32_e32 v1, s0
	s_add_i32 s0, 0, 0x20180
	ds_read_b32 v1, v1
	v_mov_b32_e32 v2, s0
	ds_read_b32 v2, v2
	s_waitcnt lgkmcnt(1)
	v_readfirstlane_b32 s0, v1
	s_lshl_b32 s0, s0, 3
	s_waitcnt lgkmcnt(0)
	v_readfirstlane_b32 s4, v2
	s_add_i32 s33, s0, s4
